# diff attention: s_setprio 1/0 around the six MFMA clusters (QK, PV for both softmax branches) so the MFMA-issuing wave wins arbitration over the partner wave's softmax VALU
# speedup vs baseline: 1.0071x; 1.0071x over previous
; #define LAS __attribute__((address_space(3)))
; DI int tidx() { int t = threadIdx.x; asm volatile("" : "+v"(t)); return t; }
; DI size_t PIDX(int row, int col) { return ((size_t)(col >> 8) * S + row) * 256 + (col & 255); }
; DI void diff_flash2(const bf16_t* proj, const bf16_t* vtc, int h, int c, int q0w, LAS unsigned char* lds, const LAS float* btab, f32x16 (&O)[4]) {
;     int tid = tidx(); asm volatile("" : "+v"(tid)); const int lane = tid & 63, r = lane & 31, hh = lane >> 5, wave = __builtin_amdgcn_readfirstlane(tid >> 6);
;     constexpr int NT = S / 64;
;     bf16x8 qf[4];
;     { const bf16_t* qp = proj + PIDX(q0w + r, C_CQKV + h * 128 + c * 64 + 8 * hh);
; #pragma unroll
;       for (int ks = 0; ks < 4; ++ks) qf[ks] = *(const bf16x8*)(qp + 16 * ks); }
; #pragma unroll
;     for (int db = 0; db < 4; ++db)
; #pragma unroll
;         for (int i = 0; i < 16; ++i) O[db][i] = 0.f;
;     float m = -1e30f, lsum = 0.f;
;     const float cs = 0.125f * LOG2E;
;     const bf16_t* kg = proj + PIDX(0, C_CQKV + 1024 + h * 128 + c * 64);
;     const bf16_t* vg = vtc + (size_t)(h * 128) * S;
;     LAS unsigned char* Kb = lds; LAS unsigned char* Vb = lds + 3 * K3BUF;
;     __syncthreads();
;     dstage_k(kg, Kb, wave, lane); dstage_v(vg, Vb, wave, lane); dstage_k(kg + (size_t)64 * 256, Kb + K3BUF, wave, lane);
;     asm volatile("s_waitcnt vmcnt(0)" ::: "memory");
;     __syncthreads();
; DI void diffattn_item(const Params& p, int l, int item, LAS unsigned char* lds) {
;     ...
;     float d01 = 0.f, d23 = 0.f;
;     for (int i = 0; i < 64; ++i) { d01 += dl[i] * dl[64 + i]; d23 += dl[128 + i] * dl[192 + i]; }
.LBB0_810:
	s_add_u32 s18, s7, s16
	s_addc_u32 s19, s8, s17
	global_load_dwordx4 v[0:3], v97, s[18:19] offset:48
	global_load_dwordx4 v[4:7], v97, s[18:19] offset:32
	global_load_dwordx4 v[8:11], v97, s[18:19] offset:16
	global_load_dwordx4 v[12:15], v97, s[18:19]
	global_load_dwordx4 v[16:19], v97, s[18:19] offset:304
	global_load_dwordx4 v[20:23], v97, s[18:19] offset:288
	global_load_dwordx4 v[24:27], v97, s[18:19] offset:272
	global_load_dwordx4 v[28:31], v97, s[18:19] offset:256
	global_load_dwordx4 v[32:35], v97, s[18:19] offset:560
	global_load_dwordx4 v[36:39], v97, s[18:19] offset:544
	global_load_dwordx4 v[40:43], v97, s[18:19] offset:528
	global_load_dwordx4 v[44:47], v97, s[18:19] offset:512
	global_load_dwordx4 v[48:51], v97, s[18:19] offset:816
	global_load_dwordx4 v[52:55], v97, s[18:19] offset:800
	global_load_dwordx4 v[56:59], v97, s[18:19] offset:784
	global_load_dwordx4 v[60:63], v97, s[18:19] offset:768
	s_add_u32 s16, s16, 64
	s_addc_u32 s17, s17, 0
	s_cmpk_eq_i32 s16, 0x100
	s_waitcnt vmcnt(12)
	v_mov_b32_e32 v64, v12
	s_waitcnt vmcnt(8)
	v_mov_b32_e32 v66, v28
	v_mov_b32_e32 v28, v14
	v_mov_b32_e32 v14, v8
	s_waitcnt vmcnt(4)
	v_mov_b32_e32 v65, v44
	v_mov_b32_e32 v44, v13
	s_waitcnt vmcnt(0)
	v_mov_b32_e32 v67, v60
	v_pk_fma_f32 v[64:65], v[64:65], v[66:67], v[162:163]
	v_mov_b32_e32 v60, v29
	v_pk_fma_f32 v[12:13], v[44:45], v[60:61], v[64:65]
	v_mov_b32_e32 v29, v46
	v_mov_b32_e32 v44, v30
	v_mov_b32_e32 v45, v62
	v_pk_fma_f32 v[12:13], v[28:29], v[44:45], v[12:13]
	v_mov_b32_e32 v46, v15
	v_mov_b32_e32 v62, v31
	v_pk_fma_f32 v[12:13], v[46:47], v[62:63], v[12:13]
	v_mov_b32_e32 v15, v40
	v_mov_b32_e32 v28, v24
	v_mov_b32_e32 v29, v56
	v_pk_fma_f32 v[12:13], v[14:15], v[28:29], v[12:13]
	v_mov_b32_e32 v40, v9
	v_mov_b32_e32 v56, v25
	v_pk_fma_f32 v[8:9], v[40:41], v[56:57], v[12:13]
	v_mov_b32_e32 v12, v10
	v_mov_b32_e32 v13, v42
	v_mov_b32_e32 v14, v26
	v_mov_b32_e32 v15, v58
	v_pk_fma_f32 v[8:9], v[12:13], v[14:15], v[8:9]
	v_mov_b32_e32 v42, v11
	v_mov_b32_e32 v58, v27
	v_pk_fma_f32 v[8:9], v[42:43], v[58:59], v[8:9]
	v_mov_b32_e32 v10, v4
	v_mov_b32_e32 v11, v36
	v_mov_b32_e32 v12, v20
	v_mov_b32_e32 v13, v52
	v_pk_fma_f32 v[8:9], v[10:11], v[12:13], v[8:9]
	v_mov_b32_e32 v36, v5
	v_mov_b32_e32 v52, v21
	v_pk_fma_f32 v[4:5], v[36:37], v[52:53], v[8:9]
	v_mov_b32_e32 v8, v6
	v_mov_b32_e32 v9, v38
	v_mov_b32_e32 v10, v22
	v_mov_b32_e32 v11, v54
	v_pk_fma_f32 v[4:5], v[8:9], v[10:11], v[4:5]
	v_mov_b32_e32 v38, v7
	v_mov_b32_e32 v54, v23
	v_pk_fma_f32 v[4:5], v[38:39], v[54:55], v[4:5]
	v_mov_b32_e32 v6, v0
	v_mov_b32_e32 v7, v32
	v_mov_b32_e32 v8, v16
	v_mov_b32_e32 v9, v48
	v_pk_fma_f32 v[4:5], v[6:7], v[8:9], v[4:5]
	v_mov_b32_e32 v32, v1
	v_mov_b32_e32 v48, v17
	v_pk_fma_f32 v[0:1], v[32:33], v[48:49], v[4:5]
	v_mov_b32_e32 v4, v2
	v_mov_b32_e32 v5, v34
	v_mov_b32_e32 v6, v18
	v_mov_b32_e32 v7, v50
	v_pk_fma_f32 v[0:1], v[4:5], v[6:7], v[0:1]
	v_mov_b32_e32 v34, v3
	v_mov_b32_e32 v50, v19
	v_pk_fma_f32 v[162:163], v[34:35], v[50:51], v[0:1]
	s_cbranch_scc0 .LBB0_810
	s_lshl_b32 s7, s55, 5
	s_and_b32 s8, s7, 0xffffff00
	v_readlane_b32 s26, v255, 41
	v_readlane_b32 s27, v255, 42
	s_add_u32 s10, s26, 0x43980000
	s_addc_u32 s11, s27, 0
	s_lshl_b32 s9, s6, 7
	s_lshl_b32 s7, s6, 20
	s_lshl_b32 s6, s6, 21
	s_or_b32 s12, s9, s7
	s_and_b32 s7, s9, 0x80
	s_and_b32 s13, s6, 0xc00000
	s_add_u32 s16, s10, s13
	s_addc_u32 s17, s11, 0
	s_add_u32 s22, s16, 0xe000000
	s_addc_u32 s23, s17, 0
	s_and_b32 s12, s12, 0x600080
	s_lshl_b32 s12, s12, 1
	s_add_u32 s20, s10, s12
	s_addc_u32 s21, s11, 0
	s_add_u32 s6, s26, s6
	s_addc_u32 s10, s27, 0
	s_add_u32 s18, s6, 0x64980000
	s_addc_u32 s19, s10, 0
	s_ashr_i32 s13, s5, 1
	v_mov_b32_e32 v26, v179
	s_andn2_b32 s13, s13, 31
	s_add_i32 s6, s13, s8
	v_writelane_b32 v255, s48, 52
	s_lshl_b32 s74, s4, 21
	v_and_b32_e32 v28, 31, v26
	v_cndmask_b32_e64 v0, 0, 1, s[48:49]
	v_bfe_u32 v29, v26, 5, 1
	v_readfirstlane_b32 s5, v0
	v_or_b32_e32 v0, s6, v28
	v_ashrrev_i32_e32 v1, 31, v0
	v_lshlrev_b64 v[0:1], 9, v[0:1]
	v_lshlrev_b32_e32 v30, 4, v29
	v_lshl_add_u64 v[0:1], s[22:23], 0, v[0:1]
	v_lshl_or_b32 v96, s7, 1, v30
	v_lshl_add_u64 v[0:1], v[0:1], 0, v[96:97]
	global_load_dwordx4 v[98:101], v[0:1], off
	global_load_dwordx4 v[102:105], v[0:1], off offset:32
	global_load_dwordx4 v[106:109], v[0:1], off offset:64
	global_load_dwordx4 v[110:113], v[0:1], off offset:96
	v_readfirstlane_b32 s4, v26
	s_ashr_i32 s4, s4, 6
	v_bfe_u32 v4, v26, 3, 3
	v_lshl_or_b32 v0, s4, 3, v4
	v_lshrrev_b32_e32 v31, 1, v0
	v_xor_b32_e32 v2, v31, v26
	v_ashrrev_i32_e32 v1, 31, v0
	v_lshlrev_b64 v[20:21], 9, v[0:1]
	v_lshlrev_b32_e32 v0, 4, v2
	v_and_b32_e32 v96, 0x70, v0
	v_lshl_add_u64 v[0:1], s[20:21], 0, v[20:21]
	v_lshl_add_u64 v[0:1], v[0:1], 0, v[96:97]
	s_mov_b64 s[10:11], 0xf000000
	v_lshl_add_u64 v[2:3], v[0:1], 0, s[10:11]
	s_lshl_b32 s11, s4, 10
	v_lshl_or_b32 v22, s4, 4, v4
	v_bfe_u32 v32, v26, 4, 2
	s_add_i32 s10, s11, 0
	v_bitop3_b32 v5, v32, v26, 63 bitop3:0x78
	v_ashrrev_i32_e32 v23, 31, v22
	s_mov_b32 m0, s10
	v_lshlrev_b64 v[24:25], 14, v[22:23]
	v_lshlrev_b32_e32 v5, 4, v5
	s_barrier
; #define LAS __attribute__((address_space(3)))
; #define MFMA32(a, b, c) __builtin_amdgcn_mfma_f32_32x32x16_bf16((a), (b), (c), 0, 0, 0)
; DI void diff_flash2(const bf16_t* proj, const bf16_t* vtc, int h, int c, int q0w, LAS unsigned char* lds, const LAS float* btab, f32x16 (&O)[4]) {
;     ...
;     dstage_k(kg, Kb, wave, lane); dstage_v(vg, Vb, wave, lane); dstage_k(kg + (size_t)64 * 256, Kb + K3BUF, wave, lane);
;     asm volatile("s_waitcnt vmcnt(0)" ::: "memory");
;     __syncthreads();
;     const int swz = (r >> 1) & 7, rowoff = r * 128;
;     int kso[4];
; #pragma unroll
;     for (int ks = 0; ks < 4; ++ks) kso[ks] = rowoff + (((2 * ks + hh) ^ swz) << 4);
;     bf16x8 kf[4], vf[8];
;     f32x16 s, sn;
; #pragma unroll
;     for (int i = 0; i < 16; ++i) s[i] = 0.f;
; #pragma unroll
;     for (int ks = 0; ks < 4; ++ks) { kf[ks] = *(const LAS bf16x8*)(Kb + kso[ks]); }
; #pragma unroll
;     for (int ks = 0; ks < 4; ++ks) s = MFMA32(kf[ks], qf[ks], s);
;     int kc = 0, kn = K3BUF, kw = 2 * K3BUF;
	global_load_lds_dwordx4 v[2:3], off
	s_lshl_b32 s24, s4, 1
	v_lshl_add_u64 v[2:3], s[18:19], 0, v[24:25]
	v_and_b32_e32 v96, 0x70, v5
	s_lshl_b32 s12, s4, 11
	s_add_i32 s4, s10, s11
	v_lshl_add_u64 v[2:3], v[2:3], 0, v[96:97]
	s_add_i32 m0, s4, 0x6000
	s_or_b32 s4, s24, 1
	global_load_lds_dwordx4 v[2:3], off
	v_lshl_or_b32 v2, s4, 3, v4
	v_lshrrev_b32_e32 v23, 1, v2
	v_xor_b32_e32 v4, v23, v26
	v_ashrrev_i32_e32 v3, 31, v2
	v_lshlrev_b64 v[2:3], 14, v[2:3]
	v_lshlrev_b32_e32 v4, 4, v4
	s_lshl_b32 s45, s4, 10
	v_lshl_add_u64 v[2:3], s[18:19], 0, v[2:3]
	v_and_b32_e32 v96, 0x70, v4
	s_add_i32 s4, s45, 0
	v_lshl_add_u64 v[2:3], v[2:3], 0, v[96:97]
	s_add_i32 m0, s4, 0x6000
	s_mov_b64 s[24:25], 0xf008000
	global_load_lds_dwordx4 v[2:3], off
	v_lshl_add_u64 v[0:1], v[0:1], 0, s[24:25]
	s_add_i32 m0, s10, 0x2000
	v_bfe_u32 v4, v26, 1, 3
	global_load_lds_dwordx4 v[0:1], off
	v_lshrrev_b32_e32 v0, 1, v26
	v_bitop3_b32 v0, v29, v0, 7 bitop3:0x78
	v_lshlrev_b32_e32 v33, 7, v28
	v_lshlrev_b32_e32 v96, 4, v0
	v_or_b32_e32 v165, v96, v33
	v_bitop3_b32 v0, v29, v4, 2 bitop3:0x36
	v_lshlrev_b32_e32 v174, 4, v0
	v_add_u32_e32 v0, 0, v165
	s_waitcnt vmcnt(0)
	s_waitcnt vmcnt(0) lgkmcnt(0)
	s_barrier
	ds_read_b128 v[0:3], v0
	v_or_b32_e32 v175, v174, v33
	v_bitop3_b32 v5, v29, v4, 4 bitop3:0x36
	v_bitop3_b32 v4, v29, v4, 6 bitop3:0x36
	v_lshlrev_b32_e32 v184, 4, v4
	v_add_u32_e32 v4, 0, v175
	v_lshlrev_b32_e32 v176, 4, v5
	ds_read_b128 v[4:7], v4
	s_waitcnt lgkmcnt(1)
	s_setprio 1
	v_mfma_f32_32x32x16_bf16 v[64:79], v[0:3], v[98:101], 0
	v_or_b32_e32 v177, v176, v33
	v_or_b32_e32 v185, v184, v33
	v_add_u32_e32 v0, 0, v177
	v_add_u32_e32 v8, 0, v185
	ds_read_b128 v[0:3], v0
	ds_read_b128 v[16:19], v8
	v_writelane_b32 v255, s49, 53
	s_lshl_b32 s5, s5, 8
	s_waitcnt lgkmcnt(2)
	v_mfma_f32_32x32x16_bf16 v[64:79], v[4:7], v[102:105], v[64:79]
	v_readlane_b32 s8, v255, 40
	s_lshl_b32 s8, s8, 21
	s_and_b32 s8, s8, 0xc00000
	s_or_b32 s5, s8, s5
	s_and_b32 s8, s50, 0xffffff00
	s_add_u32 s24, s26, s5
	s_addc_u32 s25, s27, 0
	s_waitcnt lgkmcnt(1)
	v_mfma_f32_32x32x16_bf16 v[64:79], v[0:3], v[106:109], v[64:79]
	s_add_i32 s4, s8, s13
	v_and_b32_e32 v27, 63, v26
	s_sub_i32 s11, 0, s4
	s_mov_b32 s48, 0
	s_mov_b32 s49, s48
	s_mov_b32 s15, s55
	s_mov_b32 s14, s50
	s_waitcnt lgkmcnt(0)
	v_mfma_f32_32x32x16_bf16 v[64:79], v[16:19], v[110:113], v[64:79]
	s_setprio 0
	v_bitop3_b32 v16, v31, 7, v26 bitop3:0x48
	v_lshl_or_b32 v20, v16, 4, v20
	v_lshl_add_u64 v[16:17], s[24:25], 0, v[20:21]
	s_mov_b64 s[24:25], 0x52990000
	v_or_b32_e32 v19, s4, v28
	v_lshl_add_u64 v[166:167], v[16:17], 0, s[24:25]
	v_lshlrev_b32_e32 v16, 2, v19
	v_sub_u32_e32 v16, v30, v16
	v_readlane_b32 s24, v255, 20
	v_bitop3_b32 v20, v32, 7, v27 bitop3:0x48
	v_lshlrev_b32_e32 v18, 2, v29
	v_add_u32_e32 v187, s24, v16
	s_add_u32 s24, s26, 0x64980080
	v_lshl_add_u64 v[16:17], s[74:75], 0, v[24:25]
	s_addc_u32 s25, s27, 0
	v_lshl_or_b32 v16, v20, 4, v16
	v_lshl_add_u64 v[168:169], s[24:25], 0, v[16:17]
	v_or_b32_e32 v16, 8, v22
	v_ashrrev_i32_e32 v17, 31, v16
	v_lshlrev_b64 v[16:17], 14, v[16:17]
	v_lshl_add_u64 v[16:17], s[74:75], 0, v[16:17]
	v_bitop3_b32 v20, v23, 7, v26 bitop3:0x48
	v_lshl_or_b32 v16, v20, 4, v16
	s_mov_b32 s50, s48
	s_mov_b32 s51, s48
	s_mov_b32 s52, s48
	s_mov_b32 s53, s48
	s_mov_b32 s54, s48
	s_mov_b32 s55, s48
	s_mov_b32 s56, s48
	s_mov_b32 s57, s48
	s_mov_b32 s58, s48
	s_mov_b32 s59, s48
	s_mov_b32 s60, s48
	s_mov_b32 s61, s48
	s_mov_b32 s62, s48
	s_mov_b32 s63, s48
	v_mov_b64_e32 v[0:1], s[48:49]
	v_lshl_add_u64 v[170:171], s[24:25], 0, v[16:17]
	v_sub_u32_e32 v16, v18, v28
	v_mov_b64_e32 v[14:15], s[62:63]
	v_subrev_u32_e32 v16, s13, v16
	v_mov_b64_e32 v[2:3], s[50:51]
	v_mov_b64_e32 v[4:5], s[52:53]
	v_mov_b64_e32 v[6:7], s[54:55]
	v_mov_b64_e32 v[8:9], s[56:57]
	v_mov_b64_e32 v[10:11], s[58:59]
	v_mov_b64_e32 v[12:13], s[60:61]
	v_add_u32_e32 v186, 0, v33
	v_sub_u32_e32 v188, v18, v19
	v_subrev_u32_e32 v189, s8, v16
	v_mov_b64_e32 v[30:31], v[14:15]
	v_mov_b64_e32 v[46:47], v[14:15]
	v_mov_b64_e32 v[62:63], v[14:15]
	s_movk_i32 s44, 0x2000
	v_mov_b32_e32 v191, 0xf149f2ca
	v_mov_b32_e32 v190, 0
	s_movk_i32 s49, 0x4000
	v_mov_b64_e32 v[28:29], v[12:13]
	v_mov_b64_e32 v[26:27], v[10:11]
	v_mov_b64_e32 v[24:25], v[8:9]
	v_mov_b64_e32 v[22:23], v[6:7]
	v_mov_b64_e32 v[20:21], v[4:5]
	v_mov_b64_e32 v[18:19], v[2:3]
	v_mov_b64_e32 v[16:17], v[0:1]
	v_mov_b64_e32 v[44:45], v[12:13]
	v_mov_b64_e32 v[42:43], v[10:11]
	v_mov_b64_e32 v[40:41], v[8:9]
	v_mov_b64_e32 v[38:39], v[6:7]
	v_mov_b64_e32 v[36:37], v[4:5]
	v_mov_b64_e32 v[34:35], v[2:3]
	v_mov_b64_e32 v[32:33], v[0:1]
	v_mov_b64_e32 v[60:61], v[12:13]
	v_mov_b64_e32 v[58:59], v[10:11]
	v_mov_b64_e32 v[56:57], v[8:9]
	v_mov_b64_e32 v[54:55], v[6:7]
	v_mov_b64_e32 v[52:53], v[4:5]
	v_mov_b64_e32 v[50:51], v[2:3]
	v_mov_b64_e32 v[48:49], v[0:1]
	s_movk_i32 s26, 0x4000
	s_mov_b32 s54, s44
	s_cmpk_gt_u32 s52, 0x7d
	s_mov_b32 s44, s26
	s_cbranch_scc1 .LBB0_813

; #define MFMA32(a, b, c) __builtin_amdgcn_mfma_f32_32x32x16_bf16((a), (b), (c), 0, 0, 0)
; #define DF_EXP2(i0) do { s[i0] = __builtin_amdgcn_exp2f(s[i0] * csx + c2); s[(i0) + 1] = __builtin_amdgcn_exp2f(s[(i0) + 1] * csx + c2); rs0 += s[i0]; rs1 += s[(i0) + 1]; } while (0)
; #define DF_FENCE __builtin_amdgcn_sched_barrier(0)
; DI void diff_flash2(const bf16_t* proj, const bf16_t* vtc, int h, int c, int q0w, LAS unsigned char* lds, const LAS float* btab, f32x16 (&O)[4]) {
;     ...
;             sm_max_phase(s, btab, t * 64 + 32 * half, q0w, r, hh, cs, m, lsum, O, csx, c2);
;             float rs0 = 0.f, rs1 = 0.f;
; #pragma unroll
;             for (int i = 0; i < 16; ++i) sn[i] = 0.f;
;             DF_FENCE;
;             sn = MFMA32(kf[0], qf[0], sn); DF_EXP2(0); DF_FENCE;
;             sn = MFMA32(kf[1], qf[1], sn); DF_EXP2(2); DF_FENCE;
;             sn = MFMA32(kf[2], qf[2], sn); DF_EXP2(4); DF_FENCE;
;             sn = MFMA32(kf[3], qf[3], sn); DF_EXP2(6); DF_FENCE;
;             const bf16x8 pf0 = pack8(s, 0);
;             O[0] = MFMA32(vf[0], pf0, O[0]); DF_EXP2(8); DF_FENCE;
;             O[1] = MFMA32(vf[1], pf0, O[1]); DF_EXP2(10); DF_FENCE;
;             O[2] = MFMA32(vf[2], pf0, O[2]); DF_EXP2(12); DF_FENCE;
;             O[3] = MFMA32(vf[3], pf0, O[3]); DF_EXP2(14); DF_FENCE;
;             const bf16x8 pf1 = pack8(s, 1);
;             O[0] = MFMA32(vf[4], pf1, O[0]); O[1] = MFMA32(vf[5], pf1, O[1]); O[2] = MFMA32(vf[6], pf1, O[2]); O[3] = MFMA32(vf[7], pf1, O[3]);
.LBB0_826:
	v_sub_f32_e32 v206, v172, v191
	v_fma_f32 v64, s40, v80, v206
	v_exp_f32_e32 v172, v64
	v_fma_f32 v64, s40, v81, v206
	v_exp_f32_e32 v173, v64
	s_setprio 1
	v_mfma_f32_32x32x16_bf16 v[64:79], v[126:129], v[98:101], 0
	v_mfma_f32_32x32x16_bf16 v[64:79], v[122:125], v[102:105], v[64:79]
	v_fma_f32 v80, s40, v82, v206
	v_exp_f32_e32 v193, v80
	v_fma_f32 v80, s40, v83, v206
	v_exp_f32_e32 v194, v80
	v_mfma_f32_32x32x16_bf16 v[64:79], v[118:121], v[106:109], v[64:79]
	v_fma_f32 v80, s40, v84, v206
	v_exp_f32_e32 v195, v80
	v_fma_f32 v80, s40, v85, v206
	v_exp_f32_e32 v196, v80
	v_mfma_f32_32x32x16_bf16 v[64:79], v[114:117], v[110:113], v[64:79]
	v_fma_f32 v80, s40, v86, v206
	v_exp_f32_e32 v197, v80
	v_fma_f32 v80, s40, v87, v206
	v_exp_f32_e32 v198, v80
	v_cvt_pk_bf16_f32 v80, v172, v173
	v_cvt_pk_bf16_f32 v81, v193, v194
	v_cvt_pk_bf16_f32 v82, v195, v196
	v_cvt_pk_bf16_f32 v83, v197, v198
	v_fma_f32 v84, s40, v88, v206
	v_exp_f32_e32 v199, v84
	v_mfma_f32_32x32x16_bf16 v[48:63], v[158:161], v[80:83], v[48:63]
	v_fma_f32 v84, s40, v89, v206
	v_exp_f32_e32 v200, v84
	v_mfma_f32_32x32x16_bf16 v[32:47], v[154:157], v[80:83], v[32:47]
	v_fma_f32 v84, s40, v90, v206
	v_exp_f32_e32 v201, v84
	v_fma_f32 v84, s40, v91, v206
	v_exp_f32_e32 v202, v84
	v_mfma_f32_32x32x16_bf16 v[16:31], v[150:153], v[80:83], v[16:31]
	v_fma_f32 v84, s40, v92, v206
	v_exp_f32_e32 v203, v84
	v_fma_f32 v84, s40, v93, v206
	v_exp_f32_e32 v204, v84
	v_mfma_f32_32x32x16_bf16 v[0:15], v[146:149], v[80:83], v[0:15]
	v_fma_f32 v80, s40, v94, v206
	v_fmac_f32_e32 v206, s40, v95
	v_exp_f32_e32 v205, v80
	v_exp_f32_e32 v206, v206
	v_cvt_pk_bf16_f32 v80, v199, v200
	v_cvt_pk_bf16_f32 v81, v201, v202
	v_cvt_pk_bf16_f32 v82, v203, v204
	v_cvt_pk_bf16_f32 v83, v205, v206
	s_andn2_b64 vcc, exec, s[26:27]
	s_nop 0
	v_mfma_f32_32x32x16_bf16 v[48:63], v[142:145], v[80:83], v[48:63]
	v_mfma_f32_32x32x16_bf16 v[32:47], v[130:133], v[80:83], v[32:47]
	v_mfma_f32_32x32x16_bf16 v[16:31], v[134:137], v[80:83], v[16:31]
	v_mfma_f32_32x32x16_bf16 v[0:15], v[138:141], v[80:83], v[0:15]
	s_setprio 0
	v_add_u32_e32 v80, v192, v176
	ds_read_b128 v[142:145], v80 offset:24576
	ds_read_b128 v[138:141], v80 offset:28672
	ds_read_b128 v[134:137], v80 offset:32768
	ds_read_b128 v[130:133], v80 offset:36864
	v_add_u32_e32 v80, v192, v184
	ds_read_b128 v[92:95], v80 offset:24576
	ds_read_b128 v[88:91], v80 offset:28672
	ds_read_b128 v[84:87], v80 offset:32768
	ds_read_b128 v[80:83], v80 offset:36864
	s_cbranch_vccnz .LBB0_828
	s_add_i32 s26, s54, 0
	v_add_u32_e32 v114, s26, v185
	v_add_u32_e32 v115, s26, v177
	v_add_u32_e32 v116, s26, v175
	v_add_u32_e32 v117, s26, v165
	ds_read_b128 v[126:129], v117
	ds_read_b128 v[122:125], v116
	ds_read_b128 v[118:121], v115
	ds_read_b128 v[114:117], v114

; #define MFMA32(a, b, c) __builtin_amdgcn_mfma_f32_32x32x16_bf16((a), (b), (c), 0, 0, 0)
; #define DF_EXP2(i0) do { s[i0] = __builtin_amdgcn_exp2f(s[i0] * csx + c2); s[(i0) + 1] = __builtin_amdgcn_exp2f(s[(i0) + 1] * csx + c2); rs0 += s[i0]; rs1 += s[(i0) + 1]; } while (0)
; #define DF_FENCE __builtin_amdgcn_sched_barrier(0)
; DI void diff_flash2(const bf16_t* proj, const bf16_t* vtc, int h, int c, int q0w, LAS unsigned char* lds, const LAS float* btab, f32x16 (&O)[4]) {
;     ...
;             sm_max_phase(s, btab, t * 64 + 32 * half, q0w, r, hh, cs, m, lsum, O, csx, c2);
;             float rs0 = 0.f, rs1 = 0.f;
; #pragma unroll
;             for (int i = 0; i < 16; ++i) sn[i] = 0.f;
;             DF_FENCE;
;             sn = MFMA32(kf[0], qf[0], sn); DF_EXP2(0); DF_FENCE;
;             sn = MFMA32(kf[1], qf[1], sn); DF_EXP2(2); DF_FENCE;
;             sn = MFMA32(kf[2], qf[2], sn); DF_EXP2(4); DF_FENCE;
;             sn = MFMA32(kf[3], qf[3], sn); DF_EXP2(6); DF_FENCE;
;             const bf16x8 pf0 = pack8(s, 0);
;             O[0] = MFMA32(vf[0], pf0, O[0]); DF_EXP2(8); DF_FENCE;
;             O[1] = MFMA32(vf[1], pf0, O[1]); DF_EXP2(10); DF_FENCE;
;             O[2] = MFMA32(vf[2], pf0, O[2]); DF_EXP2(12); DF_FENCE;
;             O[3] = MFMA32(vf[3], pf0, O[3]); DF_EXP2(14); DF_FENCE;
;             const bf16x8 pf1 = pack8(s, 1);
;             O[0] = MFMA32(vf[4], pf1, O[0]); O[1] = MFMA32(vf[5], pf1, O[1]); O[2] = MFMA32(vf[6], pf1, O[2]); O[3] = MFMA32(vf[7], pf1, O[3]);
;             lsum += rs0 + rs1;
;             s = sn;
;         }
;         asm volatile("s_waitcnt vmcnt(0)" ::: "memory");
;         __syncthreads();
;         const int tmp = kc; kc = kn; kn = kw; kw = tmp;
;     }
;     const float lt = lsum + __shfl_xor(lsum, 32), inv = 1.0f / lt;
; #pragma unroll
;     for (int db = 0; db < 4; ++db) O[db] *= inv;
.LBB0_839:
	v_sub_f32_e32 v161, v66, v191
	v_fma_f32 v64, s26, v64, v161
	v_exp_f32_e32 v172, v64
	v_fma_f32 v64, s26, v65, v161
	v_exp_f32_e32 v173, v64
	s_setprio 1
	v_mfma_f32_32x32x16_bf16 v[64:79], v[126:129], v[98:101], 0
	v_mfma_f32_32x32x16_bf16 v[64:79], v[122:125], v[102:105], v[64:79]
	v_fma_f32 v122, s26, v158, v161
	v_fma_f32 v123, s26, v159, v161
	v_exp_f32_e32 v122, v122
	v_exp_f32_e32 v123, v123
	v_mfma_f32_32x32x16_bf16 v[64:79], v[118:121], v[106:109], v[64:79]
	v_fma_f32 v118, s26, v156, v161
	v_fma_f32 v119, s26, v157, v161
	v_exp_f32_e32 v118, v118
	v_exp_f32_e32 v119, v119
	v_mfma_f32_32x32x16_bf16 v[64:79], v[114:117], v[110:113], v[64:79]
	v_fma_f32 v114, s26, v154, v161
	v_exp_f32_e32 v120, v114
	v_fma_f32 v114, s26, v155, v161
	v_exp_f32_e32 v121, v114
	v_fma_f32 v114, s26, v152, v161
	v_exp_f32_e32 v124, v114
	v_fma_f32 v114, s26, v153, v161
	v_exp_f32_e32 v125, v114
	v_fma_f32 v114, s26, v150, v161
	v_exp_f32_e32 v126, v114
	v_fma_f32 v114, s26, v151, v161
	v_exp_f32_e32 v127, v114
	v_fma_f32 v114, s26, v148, v161
	v_exp_f32_e32 v128, v114
	v_fma_f32 v114, s26, v149, v161
	v_exp_f32_e32 v129, v114
	v_cvt_pk_bf16_f32 v114, v172, v173
	v_cvt_pk_bf16_f32 v115, v122, v123
	v_cvt_pk_bf16_f32 v116, v118, v119
	v_cvt_pk_bf16_f32 v117, v120, v121
	s_nop 1
	v_mfma_f32_32x32x16_bf16 v[48:63], v[142:145], v[114:117], v[48:63]
	v_mfma_f32_32x32x16_bf16 v[32:47], v[138:141], v[114:117], v[32:47]
	v_add_f32_e64 v140, v172, 0
	v_add_f32_e64 v141, v173, 0
	v_fma_f32 v138, s26, v146, v161
	v_add_f32_e64 v122, v122, v140
	v_add_f32_e64 v123, v123, v141
	v_fmac_f32_e32 v161, s26, v147
	v_pk_add_f32 v[118:119], v[118:119], v[122:123]
	v_exp_f32_e32 v138, v138
	v_exp_f32_e32 v139, v161
	v_mfma_f32_32x32x16_bf16 v[16:31], v[134:137], v[114:117], v[16:31]
	v_add_f32_e64 v118, v120, v118
	v_add_f32_e64 v119, v121, v119
	v_add_f32_e64 v118, v124, v118
	v_add_f32_e64 v119, v125, v119
	v_add_f32_e64 v118, v126, v118
	v_add_f32_e64 v119, v127, v119
	v_pk_add_f32 v[118:119], v[128:129], v[118:119]
	v_mfma_f32_32x32x16_bf16 v[0:15], v[130:133], v[114:117], v[0:15]
	v_add_f32_e64 v118, v138, v118
	v_add_f32_e64 v119, v139, v119
	v_cvt_pk_bf16_f32 v114, v124, v125
	v_cvt_pk_bf16_f32 v115, v126, v127
	v_cvt_pk_bf16_f32 v116, v128, v129
	v_cvt_pk_bf16_f32 v117, v138, v139
	s_waitcnt vmcnt(0)
	s_mov_b64 s[26:27], 0x8000
	s_add_i32 s48, s48, 64
	v_mfma_f32_32x32x16_bf16 v[48:63], v[92:95], v[114:117], v[48:63]
	s_addk_i32 s49, 0x4000
	s_add_i32 s52, s52, 1
	v_lshl_add_u64 v[166:167], v[166:167], 0, s[26:27]
	v_add_u32_e32 v187, 0x100, v187
	v_lshl_add_u64 v[168:169], v[168:169], 0, s[78:79]
	v_lshl_add_u64 v[170:171], v[170:171], 0, s[78:79]
	s_cmpk_lg_i32 s48, 0x2000
	v_mfma_f32_32x32x16_bf16 v[32:47], v[88:91], v[114:117], v[32:47]
	v_add_f32_e32 v88, v118, v119
	v_add_f32_e32 v190, v160, v88
	s_waitcnt vmcnt(0)
	s_barrier
	v_mfma_f32_32x32x16_bf16 v[16:31], v[84:87], v[114:117], v[16:31]
	v_mfma_f32_32x32x16_bf16 v[0:15], v[80:83], v[114:117], v[0:15]
	s_setprio 0
	s_cbranch_scc0 .LBB0_841
	s_mov_b32 s26, s53
	s_mov_b32 s53, s54
	s_mov_b32 s54, s44
	s_cmpk_gt_u32 s52, 0x7d
	s_mov_b32 s44, s26
	s_cbranch_scc0 .LBB0_812
	s_branch .LBB0_813
.LBB0_841:
	v_lshrrev_b32_e32 v64, 3, v164
	v_cmp_lt_i32_e32 vcc, v252, v232
	v_and_or_b32 v166, v164, 31, s6
	v_and_b32_e32 v164, 4, v64
	v_cndmask_b32_e32 v64, v231, v252, vcc
	v_lshlrev_b32_e32 v165, 2, v64
	ds_bpermute_b32 v66, v165, v190
	s_lshl_b32 s10, s9, 2
	v_readlane_b32 s40, v255, 41
	v_readlane_b32 s41, v255, 42
	s_add_u32 s26, s40, s10
	v_ashrrev_i32_e32 v167, 31, v166
	s_addc_u32 s27, s41, 0
	v_lshlrev_b64 v[64:65], 12, v[166:167]
	s_waitcnt lgkmcnt(0)
	v_add_f32_e32 v66, v190, v66
	v_lshl_add_u64 v[64:65], s[26:27], 0, v[64:65]
	v_div_scale_f32 v67, s[26:27], v66, v66, 1.0
	v_rcp_f32_e32 v68, v67
	v_lshlrev_b32_e32 v96, 2, v164
	v_lshl_add_u64 v[64:65], v[64:65], 0, v[96:97]
	s_mov_b64 s[26:27], 0x76a40000
	v_fma_f32 v69, -v67, v68, 1.0
	v_fmac_f32_e32 v68, v69, v68
	v_div_scale_f32 v69, vcc, 1.0, v66, 1.0
	v_mul_f32_e32 v70, v69, v68
	v_fma_f32 v71, -v67, v70, v69
	v_fmac_f32_e32 v70, v71, v68
	v_fma_f32 v67, -v67, v70, v69
	v_div_fmas_f32 v67, v67, v68, v70
	s_mov_b32 s10, 0x76a40000
	v_lshl_add_u64 v[170:171], v[64:65], 0, s[26:27]
	v_div_fixup_f32 v66, v67, v66, 1.0
	v_add_co_u32_e32 v64, vcc, s10, v64
	v_pk_mul_f32 v[50:51], v[50:51], v[66:67] op_sel_hi:[1,0]
	v_pk_mul_f32 v[48:49], v[48:49], v[66:67] op_sel_hi:[1,0]
	v_pk_mul_f32 v[26:27], v[26:27], v[66:67] op_sel_hi:[1,0]
	v_addc_co_u32_e32 v65, vcc, 0, v65, vcc
	v_pk_mul_f32 v[62:63], v[62:63], v[66:67] op_sel_hi:[1,0]
	v_pk_mul_f32 v[60:61], v[60:61], v[66:67] op_sel_hi:[1,0]
	v_pk_mul_f32 v[58:59], v[58:59], v[66:67] op_sel_hi:[1,0]
	v_pk_mul_f32 v[56:57], v[56:57], v[66:67] op_sel_hi:[1,0]
	v_pk_mul_f32 v[54:55], v[54:55], v[66:67] op_sel_hi:[1,0]
	v_pk_mul_f32 v[52:53], v[52:53], v[66:67] op_sel_hi:[1,0]
	v_pk_mul_f32 v[46:47], v[46:47], v[66:67] op_sel_hi:[1,0]
	v_pk_mul_f32 v[44:45], v[44:45], v[66:67] op_sel_hi:[1,0]
	v_pk_mul_f32 v[42:43], v[42:43], v[66:67] op_sel_hi:[1,0]
	v_pk_mul_f32 v[40:41], v[40:41], v[66:67] op_sel_hi:[1,0]
	v_pk_mul_f32 v[38:39], v[38:39], v[66:67] op_sel_hi:[1,0]
	v_pk_mul_f32 v[36:37], v[36:37], v[66:67] op_sel_hi:[1,0]
	v_pk_mul_f32 v[34:35], v[34:35], v[66:67] op_sel_hi:[1,0]
	v_pk_mul_f32 v[32:33], v[32:33], v[66:67] op_sel_hi:[1,0]
	v_pk_mul_f32 v[30:31], v[30:31], v[66:67] op_sel_hi:[1,0]
	v_pk_mul_f32 v[28:29], v[28:29], v[66:67] op_sel_hi:[1,0]
	v_pk_mul_f32 v[24:25], v[24:25], v[66:67] op_sel_hi:[1,0]
	v_pk_mul_f32 v[22:23], v[22:23], v[66:67] op_sel_hi:[1,0]
	v_pk_mul_f32 v[20:21], v[20:21], v[66:67] op_sel_hi:[1,0]
; #define LAS __attribute__((address_space(3)))
; DI size_t PIDX(int row, int col) { return ((size_t)(col >> 8) * S + row) * 256 + (col & 255); }
; DI void diff_flash2(const bf16_t* proj, const bf16_t* vtc, int h, int c, int q0w, LAS unsigned char* lds, const LAS float* btab, f32x16 (&O)[4]) {
;     ...
;     { const bf16_t* qp = proj + PIDX(q0w + r, C_CQKV + h * 128 + c * 64 + 8 * hh);
; #pragma unroll
;       for (int ks = 0; ks < 4; ++ks) qf[ks] = *(const bf16x8*)(qp + 16 * ks); }
; #pragma unroll
;     for (int db = 0; db < 4; ++db)
; #pragma unroll
;         for (int i = 0; i < 16; ++i) O[db][i] = 0.f;
;     float m = -1e30f, lsum = 0.f;
;     const float cs = 0.125f * LOG2E;
;     const bf16_t* kg = proj + PIDX(0, C_CQKV + 1024 + h * 128 + c * 64);
;     const bf16_t* vg = vtc + (size_t)(h * 128) * S;
;     LAS unsigned char* Kb = lds; LAS unsigned char* Vb = lds + 3 * K3BUF;
;     __syncthreads();
;     dstage_k(kg, Kb, wave, lane); dstage_v(vg, Vb, wave, lane); dstage_k(kg + (size_t)64 * 256, Kb + K3BUF, wave, lane);
;     asm volatile("s_waitcnt vmcnt(0)" ::: "memory");
;     __syncthreads();
; DI void diffattn_item(const Params& p, int l, int item, LAS unsigned char* lds) {
;     ...
;     for (int db = 0; db < 4; ++db)
; #pragma unroll
;         for (int i4 = 0; i4 < 4; ++i4) { f32x4 o = {O0[db][4 * i4], O0[db][4 * i4 + 1], O0[db][4 * i4 + 2], O0[db][4 * i4 + 3]}; *(f32x4*)(ctmp + 32 * db + 8 * i4) = o; }
	v_pk_mul_f32 v[18:19], v[18:19], v[66:67] op_sel_hi:[1,0]
	v_pk_mul_f32 v[16:17], v[16:17], v[66:67] op_sel_hi:[1,0]
	v_pk_mul_f32 v[14:15], v[14:15], v[66:67] op_sel_hi:[1,0]
	v_pk_mul_f32 v[12:13], v[12:13], v[66:67] op_sel_hi:[1,0]
	v_pk_mul_f32 v[10:11], v[10:11], v[66:67] op_sel_hi:[1,0]
	v_pk_mul_f32 v[8:9], v[8:9], v[66:67] op_sel_hi:[1,0]
	v_pk_mul_f32 v[6:7], v[6:7], v[66:67] op_sel_hi:[1,0]
	v_pk_mul_f32 v[4:5], v[4:5], v[66:67] op_sel_hi:[1,0]
	v_pk_mul_f32 v[2:3], v[2:3], v[66:67] op_sel_hi:[1,0]
	v_pk_mul_f32 v[0:1], v[0:1], v[66:67] op_sel_hi:[1,0]
	global_store_dwordx4 v[64:65], v[48:51], off
	global_store_dwordx4 v[170:171], v[52:55], off offset:32
	global_store_dwordx4 v[170:171], v[56:59], off offset:64
	global_store_dwordx4 v[170:171], v[60:63], off offset:96
	global_store_dwordx4 v[170:171], v[32:35], off offset:128
	global_store_dwordx4 v[170:171], v[36:39], off offset:160
	global_store_dwordx4 v[170:171], v[40:43], off offset:192
	global_store_dwordx4 v[170:171], v[44:47], off offset:224
	global_store_dwordx4 v[170:171], v[16:19], off offset:256
	global_store_dwordx4 v[170:171], v[20:23], off offset:288
	global_store_dwordx4 v[170:171], v[24:27], off offset:320
	global_store_dwordx4 v[170:171], v[28:31], off offset:352
	global_store_dwordx4 v[170:171], v[0:3], off offset:384
	global_store_dwordx4 v[170:171], v[4:7], off offset:416
	global_store_dwordx4 v[170:171], v[8:11], off offset:448
	global_store_dwordx4 v[170:171], v[12:15], off offset:480
	v_mov_b32_e32 v26, v179
	s_mov_b32 s48, 0
	s_mov_b32 s49, s48
	v_and_b32_e32 v28, 31, v26
	v_or_b32_e32 v0, s6, v28
	v_bfe_u32 v29, v26, 5, 1
	v_ashrrev_i32_e32 v1, 31, v0
	v_lshlrev_b64 v[0:1], 9, v[0:1]
	v_lshlrev_b32_e32 v30, 4, v29
	v_lshl_add_u64 v[0:1], s[22:23], 0, v[0:1]
	v_lshl_or_b32 v96, s7, 1, v30
	v_lshl_add_u64 v[0:1], v[0:1], 0, v[96:97]
	global_load_dwordx4 v[98:101], v[0:1], off offset:128
	global_load_dwordx4 v[102:105], v[0:1], off offset:160
	global_load_dwordx4 v[106:109], v[0:1], off offset:192
	global_load_dwordx4 v[110:113], v[0:1], off offset:224
	v_readfirstlane_b32 s10, v26
	s_ashr_i32 s10, s10, 6
	v_bfe_u32 v4, v26, 3, 3
	v_lshl_or_b32 v0, s10, 3, v4
	v_lshrrev_b32_e32 v31, 1, v0
	v_xor_b32_e32 v2, v31, v26
	v_ashrrev_i32_e32 v1, 31, v0
	v_lshlrev_b64 v[20:21], 9, v[0:1]
	v_lshlrev_b32_e32 v0, 4, v2
	v_and_b32_e32 v96, 0x70, v0
	v_lshl_add_u64 v[0:1], s[20:21], 0, v[20:21]
	s_lshl_b32 s12, s10, 10
	v_lshl_or_b32 v22, s10, 4, v4
	v_bfe_u32 v32, v26, 4, 2
	v_lshl_add_u64 v[0:1], v[0:1], 0, v[96:97]
	s_mov_b64 s[20:21], 0xf000080
	s_add_i32 s6, s12, 0
	v_bitop3_b32 v5, v32, v26, 63 bitop3:0x78
	v_ashrrev_i32_e32 v23, 31, v22
	v_lshl_add_u64 v[2:3], v[0:1], 0, s[20:21]
	s_mov_b32 m0, s6
	v_lshlrev_b64 v[24:25], 14, v[22:23]
	v_lshlrev_b32_e32 v5, 4, v5
	s_barrier
	global_load_lds_dwordx4 v[2:3], off
	s_lshl_b32 s20, s10, 1
	v_lshl_add_u64 v[2:3], s[18:19], 0, v[24:25]
	v_and_b32_e32 v96, 0x70, v5
	s_add_i32 s12, s6, s12
	v_lshl_add_u64 v[2:3], v[2:3], 0, v[96:97]
	s_add_i32 m0, s12, 0x6000
	s_or_b32 s12, s20, 1
	global_load_lds_dwordx4 v[2:3], off
	v_lshl_or_b32 v2, s12, 3, v4
	v_lshrrev_b32_e32 v23, 1, v2
	v_xor_b32_e32 v4, v23, v26
	v_ashrrev_i32_e32 v3, 31, v2
	v_lshlrev_b64 v[2:3], 14, v[2:3]
	v_lshlrev_b32_e32 v4, 4, v4
	s_lshl_b32 s12, s12, 10
	v_lshl_add_u64 v[2:3], s[18:19], 0, v[2:3]
	v_and_b32_e32 v96, 0x70, v4
	s_add_i32 s18, s12, 0
	v_lshl_add_u64 v[2:3], v[2:3], 0, v[96:97]
	s_add_i32 m0, s18, 0x6000
	s_mov_b64 s[18:19], 0xf008080
	global_load_lds_dwordx4 v[2:3], off
	v_lshl_add_u64 v[0:1], v[0:1], 0, s[18:19]
	s_add_i32 m0, s6, 0x2000
	v_bfe_u32 v4, v26, 1, 3
	global_load_lds_dwordx4 v[0:1], off
	v_lshrrev_b32_e32 v0, 1, v26
	v_bitop3_b32 v0, v29, v0, 7 bitop3:0x78
	v_lshlrev_b32_e32 v33, 7, v28
	v_lshlrev_b32_e32 v186, 4, v0
	v_or_b32_e32 v187, v186, v33
	v_bitop3_b32 v0, v29, v4, 2 bitop3:0x36
	v_lshlrev_b32_e32 v188, 4, v0
	v_add_u32_e32 v0, 0, v187
	s_waitcnt vmcnt(0)
	s_waitcnt vmcnt(0) lgkmcnt(0)
	s_barrier
; #define LAS __attribute__((address_space(3)))
; #define MFMA32(a, b, c) __builtin_amdgcn_mfma_f32_32x32x16_bf16((a), (b), (c), 0, 0, 0)
; DI void diff_flash2(const bf16_t* proj, const bf16_t* vtc, int h, int c, int q0w, LAS unsigned char* lds, const LAS float* btab, f32x16 (&O)[4]) {
;     ...
;     const int swz = (r >> 1) & 7, rowoff = r * 128;
;     int kso[4];
; #pragma unroll
;     for (int ks = 0; ks < 4; ++ks) kso[ks] = rowoff + (((2 * ks + hh) ^ swz) << 4);
;     bf16x8 kf[4], vf[8];
;     f32x16 s, sn;
; #pragma unroll
;     for (int i = 0; i < 16; ++i) s[i] = 0.f;
; #pragma unroll
;     for (int ks = 0; ks < 4; ++ks) { kf[ks] = *(const LAS bf16x8*)(Kb + kso[ks]); }
; #pragma unroll
;     for (int ks = 0; ks < 4; ++ks) s = MFMA32(kf[ks], qf[ks], s);
;     int kc = 0, kn = K3BUF, kw = 2 * K3BUF;
	ds_read_b128 v[0:3], v0
	v_or_b32_e32 v189, v188, v33
	v_bitop3_b32 v5, v29, v4, 4 bitop3:0x36
	v_bitop3_b32 v4, v29, v4, 6 bitop3:0x36
	v_lshlrev_b32_e32 v192, 4, v4
	v_add_u32_e32 v4, 0, v189
	v_lshlrev_b32_e32 v190, 4, v5
	ds_read_b128 v[4:7], v4
	s_waitcnt lgkmcnt(1)
	s_setprio 1
	v_mfma_f32_32x32x16_bf16 v[64:79], v[0:3], v[98:101], 0
	v_or_b32_e32 v191, v190, v33
	v_or_b32_e32 v193, v192, v33
	v_add_u32_e32 v0, 0, v191
	v_add_u32_e32 v8, 0, v193
	ds_read_b128 v[0:3], v0
	ds_read_b128 v[16:19], v8
	s_lshl_b32 s10, s10, 11
	s_add_u32 s18, s40, s5
	s_waitcnt lgkmcnt(2)
	v_mfma_f32_32x32x16_bf16 v[64:79], v[4:7], v[102:105], v[64:79]
	s_addc_u32 s19, s41, 0
	v_and_b32_e32 v27, 63, v26
	s_mov_b32 s50, s48
	s_mov_b32 s51, s48
	s_mov_b32 s52, s48
	s_mov_b32 s53, s48
	s_mov_b32 s54, s48
	s_waitcnt lgkmcnt(1)
	v_mfma_f32_32x32x16_bf16 v[64:79], v[0:3], v[106:109], v[64:79]
	s_mov_b32 s55, s48
	s_mov_b32 s56, s48
	s_mov_b32 s57, s48
	s_mov_b32 s58, s48
	s_mov_b32 s59, s48
	s_mov_b32 s60, s48
	s_mov_b32 s61, s48
	s_waitcnt lgkmcnt(0)
	v_mfma_f32_32x32x16_bf16 v[64:79], v[16:19], v[110:113], v[64:79]
	s_setprio 0
	v_bitop3_b32 v16, v31, 7, v26 bitop3:0x48
	v_lshl_or_b32 v20, v16, 4, v20
	v_lshl_add_u64 v[16:17], s[18:19], 0, v[20:21]
	s_mov_b64 s[18:19], 0x52990080
	v_add_u32_e32 v19, s4, v28
	v_lshl_add_u64 v[172:173], v[16:17], 0, s[18:19]
	v_lshlrev_b32_e32 v16, 2, v19
	v_sub_u32_e32 v16, v30, v16
	v_readlane_b32 s4, v255, 20
	v_bitop3_b32 v20, v32, 7, v27 bitop3:0x48
	v_lshlrev_b32_e32 v96, 4, v20
	v_add_u32_e32 v195, s4, v16
	v_lshl_add_u64 v[16:17], s[74:75], 0, v[24:25]
	v_lshl_add_u64 v[16:17], v[16:17], 0, v[96:97]
	v_lshl_add_u64 v[174:175], s[24:25], 0, v[16:17]
	v_or_b32_e32 v16, 8, v22
	v_ashrrev_i32_e32 v17, 31, v16
	v_lshlrev_b64 v[16:17], 14, v[16:17]
	v_bitop3_b32 v20, v23, 7, v26 bitop3:0x48
	v_lshl_add_u64 v[16:17], s[74:75], 0, v[16:17]
	v_lshlrev_b32_e32 v96, 4, v20
	v_lshlrev_b32_e32 v18, 2, v29
	v_lshl_add_u64 v[16:17], v[16:17], 0, v[96:97]
	s_mov_b32 s62, s48
	s_mov_b32 s63, s48
	v_mov_b64_e32 v[0:1], s[48:49]
	v_lshl_add_u64 v[176:177], s[24:25], 0, v[16:17]
	v_sub_u32_e32 v16, v18, v28
	v_mov_b64_e32 v[2:3], s[50:51]
	v_mov_b64_e32 v[4:5], s[52:53]
	v_mov_b64_e32 v[6:7], s[54:55]
	v_mov_b64_e32 v[8:9], s[56:57]
	v_mov_b64_e32 v[10:11], s[58:59]
	v_mov_b64_e32 v[12:13], s[60:61]
	v_mov_b64_e32 v[14:15], s[62:63]
	v_subrev_u32_e32 v16, s13, v16
	v_readlane_b32 s62, v255, 31
	v_add_u32_e32 v194, 0, v33
	v_sub_u32_e32 v96, v18, v19
	v_subrev_u32_e32 v196, s8, v16
	v_mov_b64_e32 v[30:31], v[14:15]
	v_mov_b64_e32 v[46:47], v[14:15]
	v_mov_b64_e32 v[62:63], v[14:15]
	v_readlane_b32 s63, v255, 32
	v_readlane_b32 s52, v255, 48
	v_lshlrev_b64 v[168:169], 10, v[166:167]
	s_mov_b32 s27, 0x9000000
	s_movk_i32 s26, 0x2000
	v_mov_b32_e32 v198, 0xf149f2ca
	v_mov_b32_e32 v197, 0
	s_movk_i32 s4, 0x4000
	v_mov_b64_e32 v[28:29], v[12:13]
	v_mov_b64_e32 v[26:27], v[10:11]
	v_mov_b64_e32 v[24:25], v[8:9]
	v_mov_b64_e32 v[22:23], v[6:7]
	v_mov_b64_e32 v[20:21], v[4:5]
	v_mov_b64_e32 v[18:19], v[2:3]
	v_mov_b64_e32 v[16:17], v[0:1]
	v_mov_b64_e32 v[44:45], v[12:13]
	v_mov_b64_e32 v[42:43], v[10:11]
	v_mov_b64_e32 v[40:41], v[8:9]
	v_mov_b64_e32 v[38:39], v[6:7]
	v_mov_b64_e32 v[36:37], v[4:5]
	v_mov_b64_e32 v[34:35], v[2:3]
	v_mov_b64_e32 v[32:33], v[0:1]
	v_mov_b64_e32 v[60:61], v[12:13]
	v_mov_b64_e32 v[58:59], v[10:11]
	v_mov_b64_e32 v[56:57], v[8:9]
	v_mov_b64_e32 v[54:55], v[6:7]
	v_mov_b64_e32 v[52:53], v[4:5]
	v_mov_b64_e32 v[50:51], v[2:3]
	v_mov_b64_e32 v[48:49], v[0:1]
	s_mov_b32 s5, s48
	s_movk_i32 s18, 0x4000
	s_mov_b32 s8, s48
	v_readlane_b32 s61, v255, 33
	s_movk_i32 s44, 0x400
	s_movk_i32 s63, 0x2000
	s_movk_i32 s45, 0x1000
	s_mov_b32 s60, 0x78a5c000
	s_mov_b32 s51, 0x409b43d5
	v_readlane_b32 s53, v255, 49
	s_mov_b32 s50, s14
	s_mov_b32 s54, s96
	s_movk_i32 s96, 0xd400
	s_mov_b32 s56, s84
	s_movk_i32 s84, 0xd200
	s_mov_b32 s58, s2
	s_mov_b32 s55, s15
	s_mov_b32 s13, s26
	s_cmpk_gt_u32 s5, 0x7d
	s_mov_b32 s26, s18
	s_cbranch_scc1 .LBB0_843

; #define MFMA32(a, b, c) __builtin_amdgcn_mfma_f32_32x32x16_bf16((a), (b), (c), 0, 0, 0)
; #define DF_EXP2(i0) do { s[i0] = __builtin_amdgcn_exp2f(s[i0] * csx + c2); s[(i0) + 1] = __builtin_amdgcn_exp2f(s[(i0) + 1] * csx + c2); rs0 += s[i0]; rs1 += s[(i0) + 1]; } while (0)
; #define DF_FENCE __builtin_amdgcn_sched_barrier(0)
; DI void diff_flash2(const bf16_t* proj, const bf16_t* vtc, int h, int c, int q0w, LAS unsigned char* lds, const LAS float* btab, f32x16 (&O)[4]) {
;     ...
;             sm_max_phase(s, btab, t * 64 + 32 * half, q0w, r, hh, cs, m, lsum, O, csx, c2);
;             float rs0 = 0.f, rs1 = 0.f;
; #pragma unroll
;             for (int i = 0; i < 16; ++i) sn[i] = 0.f;
;             DF_FENCE;
;             sn = MFMA32(kf[0], qf[0], sn); DF_EXP2(0); DF_FENCE;
;             sn = MFMA32(kf[1], qf[1], sn); DF_EXP2(2); DF_FENCE;
;             sn = MFMA32(kf[2], qf[2], sn); DF_EXP2(4); DF_FENCE;
;             sn = MFMA32(kf[3], qf[3], sn); DF_EXP2(6); DF_FENCE;
;             const bf16x8 pf0 = pack8(s, 0);
;             O[0] = MFMA32(vf[0], pf0, O[0]); DF_EXP2(8); DF_FENCE;
;             O[1] = MFMA32(vf[1], pf0, O[1]); DF_EXP2(10); DF_FENCE;
;             O[2] = MFMA32(vf[2], pf0, O[2]); DF_EXP2(12); DF_FENCE;
;             O[3] = MFMA32(vf[3], pf0, O[3]); DF_EXP2(14); DF_FENCE;
;             const bf16x8 pf1 = pack8(s, 1);
;             O[0] = MFMA32(vf[4], pf1, O[0]); O[1] = MFMA32(vf[5], pf1, O[1]); O[2] = MFMA32(vf[6], pf1, O[2]); O[3] = MFMA32(vf[7], pf1, O[3]);
.LBB0_856:
	v_sub_f32_e32 v213, v184, v198
	v_fma_f32 v64, s20, v80, v213
	v_exp_f32_e32 v184, v64
	v_fma_f32 v64, s20, v81, v213
	v_exp_f32_e32 v185, v64
	s_setprio 1
	v_mfma_f32_32x32x16_bf16 v[64:79], v[126:129], v[98:101], 0
	v_mfma_f32_32x32x16_bf16 v[64:79], v[122:125], v[102:105], v[64:79]
	v_fma_f32 v80, s20, v82, v213
	v_exp_f32_e32 v200, v80
	v_fma_f32 v80, s20, v83, v213
	v_exp_f32_e32 v201, v80
	v_mfma_f32_32x32x16_bf16 v[64:79], v[118:121], v[106:109], v[64:79]
	v_fma_f32 v80, s20, v84, v213
	v_exp_f32_e32 v202, v80
	v_fma_f32 v80, s20, v85, v213
	v_exp_f32_e32 v203, v80
	v_mfma_f32_32x32x16_bf16 v[64:79], v[114:117], v[110:113], v[64:79]
	v_fma_f32 v80, s20, v86, v213
	v_exp_f32_e32 v204, v80
	v_fma_f32 v80, s20, v87, v213
	v_exp_f32_e32 v205, v80
	v_cvt_pk_bf16_f32 v80, v184, v185
	v_cvt_pk_bf16_f32 v81, v200, v201
	v_cvt_pk_bf16_f32 v82, v202, v203
	v_cvt_pk_bf16_f32 v83, v204, v205
	v_fma_f32 v84, s20, v88, v213
	v_exp_f32_e32 v206, v84
	v_mfma_f32_32x32x16_bf16 v[48:63], v[158:161], v[80:83], v[48:63]
	v_fma_f32 v84, s20, v89, v213
	v_exp_f32_e32 v207, v84
	v_mfma_f32_32x32x16_bf16 v[32:47], v[154:157], v[80:83], v[32:47]
	v_fma_f32 v84, s20, v90, v213
	v_exp_f32_e32 v208, v84
	v_fma_f32 v84, s20, v91, v213
	v_exp_f32_e32 v209, v84
	v_mfma_f32_32x32x16_bf16 v[16:31], v[150:153], v[80:83], v[16:31]
	v_fma_f32 v84, s20, v92, v213
	v_exp_f32_e32 v210, v84
	v_fma_f32 v84, s20, v93, v213
	v_exp_f32_e32 v211, v84
	v_mfma_f32_32x32x16_bf16 v[0:15], v[146:149], v[80:83], v[0:15]
	v_fma_f32 v80, s20, v94, v213
	v_fmac_f32_e32 v213, s20, v95
	v_exp_f32_e32 v212, v80
	v_exp_f32_e32 v213, v213
	v_cvt_pk_bf16_f32 v80, v206, v207
	v_cvt_pk_bf16_f32 v81, v208, v209
	v_cvt_pk_bf16_f32 v82, v210, v211
	v_cvt_pk_bf16_f32 v83, v212, v213
	s_andn2_b64 vcc, exec, s[18:19]
	s_nop 0
	v_mfma_f32_32x32x16_bf16 v[48:63], v[142:145], v[80:83], v[48:63]
	v_mfma_f32_32x32x16_bf16 v[32:47], v[130:133], v[80:83], v[32:47]
	v_mfma_f32_32x32x16_bf16 v[16:31], v[134:137], v[80:83], v[16:31]
	v_mfma_f32_32x32x16_bf16 v[0:15], v[138:141], v[80:83], v[0:15]
	s_setprio 0
	v_add_u32_e32 v80, v199, v190
	ds_read_b128 v[142:145], v80 offset:24576
	ds_read_b128 v[138:141], v80 offset:28672
	ds_read_b128 v[134:137], v80 offset:32768
	ds_read_b128 v[130:133], v80 offset:36864
	v_add_u32_e32 v80, v199, v192
	ds_read_b128 v[92:95], v80 offset:24576
	ds_read_b128 v[88:91], v80 offset:28672
	ds_read_b128 v[84:87], v80 offset:32768
	ds_read_b128 v[80:83], v80 offset:36864
	s_cbranch_vccnz .LBB0_858
	s_add_i32 s18, s13, 0
	v_add_u32_e32 v114, s18, v193
	v_add_u32_e32 v115, s18, v191
	v_add_u32_e32 v116, s18, v189
	v_add_u32_e32 v117, s18, v187
	ds_read_b128 v[126:129], v117
	ds_read_b128 v[122:125], v116
	ds_read_b128 v[118:121], v115
	ds_read_b128 v[114:117], v114

; #define MFMA32(a, b, c) __builtin_amdgcn_mfma_f32_32x32x16_bf16((a), (b), (c), 0, 0, 0)
; #define DF_EXP2(i0) do { s[i0] = __builtin_amdgcn_exp2f(s[i0] * csx + c2); s[(i0) + 1] = __builtin_amdgcn_exp2f(s[(i0) + 1] * csx + c2); rs0 += s[i0]; rs1 += s[(i0) + 1]; } while (0)
; #define DF_FENCE __builtin_amdgcn_sched_barrier(0)
; DI void diff_flash2(const bf16_t* proj, const bf16_t* vtc, int h, int c, int q0w, LAS unsigned char* lds, const LAS float* btab, f32x16 (&O)[4]) {
;     ...
;             sm_max_phase(s, btab, t * 64 + 32 * half, q0w, r, hh, cs, m, lsum, O, csx, c2);
;             float rs0 = 0.f, rs1 = 0.f;
; #pragma unroll
;             for (int i = 0; i < 16; ++i) sn[i] = 0.f;
;             DF_FENCE;
;             sn = MFMA32(kf[0], qf[0], sn); DF_EXP2(0); DF_FENCE;
;             sn = MFMA32(kf[1], qf[1], sn); DF_EXP2(2); DF_FENCE;
;             sn = MFMA32(kf[2], qf[2], sn); DF_EXP2(4); DF_FENCE;
;             sn = MFMA32(kf[3], qf[3], sn); DF_EXP2(6); DF_FENCE;
;             const bf16x8 pf0 = pack8(s, 0);
;             O[0] = MFMA32(vf[0], pf0, O[0]); DF_EXP2(8); DF_FENCE;
;             O[1] = MFMA32(vf[1], pf0, O[1]); DF_EXP2(10); DF_FENCE;
;             O[2] = MFMA32(vf[2], pf0, O[2]); DF_EXP2(12); DF_FENCE;
;             O[3] = MFMA32(vf[3], pf0, O[3]); DF_EXP2(14); DF_FENCE;
;             const bf16x8 pf1 = pack8(s, 1);
;             O[0] = MFMA32(vf[4], pf1, O[0]); O[1] = MFMA32(vf[5], pf1, O[1]); O[2] = MFMA32(vf[6], pf1, O[2]); O[3] = MFMA32(vf[7], pf1, O[3]);
;             lsum += rs0 + rs1;
;             s = sn;
;         }
;         asm volatile("s_waitcnt vmcnt(0)" ::: "memory");
;         __syncthreads();
;         const int tmp = kc; kc = kn; kn = kw; kw = tmp;
;     }
.LBB0_869:
	v_sub_f32_e32 v161, v66, v198
	v_fma_f32 v64, s18, v64, v161
	v_exp_f32_e32 v184, v64
	v_fma_f32 v64, s18, v65, v161
	v_exp_f32_e32 v185, v64
	s_setprio 1
	v_mfma_f32_32x32x16_bf16 v[64:79], v[126:129], v[98:101], 0
	v_mfma_f32_32x32x16_bf16 v[64:79], v[122:125], v[102:105], v[64:79]
	v_fma_f32 v122, s18, v158, v161
	v_fma_f32 v123, s18, v159, v161
	v_exp_f32_e32 v122, v122
	v_exp_f32_e32 v123, v123
	v_mfma_f32_32x32x16_bf16 v[64:79], v[118:121], v[106:109], v[64:79]
	v_fma_f32 v118, s18, v156, v161
	v_fma_f32 v119, s18, v157, v161
	v_exp_f32_e32 v118, v118
	v_exp_f32_e32 v119, v119
	v_mfma_f32_32x32x16_bf16 v[64:79], v[114:117], v[110:113], v[64:79]
	v_fma_f32 v114, s18, v154, v161
	v_exp_f32_e32 v120, v114
	v_fma_f32 v114, s18, v155, v161
	v_exp_f32_e32 v121, v114
	v_fma_f32 v114, s18, v152, v161
	v_exp_f32_e32 v124, v114
	v_fma_f32 v114, s18, v153, v161
	v_exp_f32_e32 v125, v114
	v_fma_f32 v114, s18, v150, v161
	v_exp_f32_e32 v126, v114
	v_fma_f32 v114, s18, v151, v161
	v_exp_f32_e32 v127, v114
	v_fma_f32 v114, s18, v148, v161
	v_exp_f32_e32 v128, v114
	v_fma_f32 v114, s18, v149, v161
	v_exp_f32_e32 v129, v114
	v_cvt_pk_bf16_f32 v114, v184, v185
	v_cvt_pk_bf16_f32 v115, v122, v123
	v_cvt_pk_bf16_f32 v116, v118, v119
	v_cvt_pk_bf16_f32 v117, v120, v121
	s_nop 1
	v_mfma_f32_32x32x16_bf16 v[48:63], v[142:145], v[114:117], v[48:63]
	v_mfma_f32_32x32x16_bf16 v[32:47], v[138:141], v[114:117], v[32:47]
	v_add_f32_e64 v140, v184, 0
	v_add_f32_e64 v141, v185, 0
	v_fma_f32 v138, s18, v146, v161
	v_add_f32_e64 v122, v122, v140
	v_add_f32_e64 v123, v123, v141
	v_fmac_f32_e32 v161, s18, v147
	v_pk_add_f32 v[118:119], v[118:119], v[122:123]
	v_exp_f32_e32 v138, v138
	v_exp_f32_e32 v139, v161
	v_mfma_f32_32x32x16_bf16 v[16:31], v[134:137], v[114:117], v[16:31]
	v_add_f32_e64 v118, v120, v118
	v_add_f32_e64 v119, v121, v119
	v_add_f32_e64 v118, v124, v118
	v_add_f32_e64 v119, v125, v119
	v_add_f32_e64 v118, v126, v118
	v_add_f32_e64 v119, v127, v119
	v_pk_add_f32 v[118:119], v[128:129], v[118:119]
	v_mfma_f32_32x32x16_bf16 v[0:15], v[130:133], v[114:117], v[0:15]
	v_add_f32_e64 v118, v138, v118
	v_add_f32_e64 v119, v139, v119
	v_cvt_pk_bf16_f32 v114, v124, v125
	v_cvt_pk_bf16_f32 v115, v126, v127
	v_cvt_pk_bf16_f32 v116, v128, v129
	v_cvt_pk_bf16_f32 v117, v138, v139
	s_waitcnt vmcnt(0)
	s_mov_b64 s[18:19], 0x8000
	s_add_i32 s48, s48, 64
	v_mfma_f32_32x32x16_bf16 v[48:63], v[92:95], v[114:117], v[48:63]
	s_addk_i32 s4, 0x4000
	s_add_i32 s5, s5, 1
	v_lshl_add_u64 v[172:173], v[172:173], 0, s[18:19]
	v_add_u32_e32 v195, 0x100, v195
	v_lshl_add_u64 v[174:175], v[174:175], 0, s[78:79]
	v_lshl_add_u64 v[176:177], v[176:177], 0, s[78:79]
	s_cmpk_lg_i32 s48, 0x2000
	v_mfma_f32_32x32x16_bf16 v[32:47], v[88:91], v[114:117], v[32:47]
	v_add_f32_e32 v88, v118, v119
	v_add_f32_e32 v197, v160, v88
	s_waitcnt vmcnt(0)
	s_barrier
	v_mfma_f32_32x32x16_bf16 v[16:31], v[84:87], v[114:117], v[16:31]
	v_mfma_f32_32x32x16_bf16 v[0:15], v[80:83], v[114:117], v[0:15]
	s_setprio 0
	s_cbranch_scc0 .LBB0_551
	s_mov_b32 s18, s8
	s_mov_b32 s8, s13
	s_mov_b32 s13, s26
	s_cmpk_gt_u32 s5, 0x7d
	s_mov_b32 s26, s18
	s_cbranch_scc0 .LBB0_842
	s_branch .LBB0_843
